# m23 with back-off polling: s_sleep 4 instead of s_sleep 1 in the 36 grid-barrier spin loops
# baseline (speedup 1.0000x reference)
; __device__ __forceinline__ unsigned xb_ld(unsigned* p)              { return __hip_atomic_load(p, __ATOMIC_RELAXED, __HIP_MEMORY_SCOPE_AGENT); }
; __device__ __forceinline__ void xcd_barrier_complete(unsigned* bar, unsigned x, unsigned& nloc, unsigned& nx) {
;     const unsigned G = gridDim.x * gridDim.y * gridDim.z;
;     unsigned sum, cnt, mine, sp = 0u;
;     for (;;) {
;         sum = 0u; cnt = 0u; mine = 0u;
; #pragma unroll
;         for (unsigned j = 0; j < 16; ++j) { const unsigned c = xb_ld(&bar[XB_XCNT(j)]); sum += c; cnt += (c > 0u) ? 1u : 0u; mine = (j == x) ? c : mine; }
;         if (sum == G) break;
;         __builtin_amdgcn_s_sleep(1);
;         if ((++sp & 255u) == 0u) { if (xb_ld(&bar[XB_TMO])) break; if (sp > XB_SPIN_CAP) { atomicAdd(&bar[XB_TMO], 1u); break; } }
;     }
.LBB11_166:
	global_load_dword v16, v17, s[8:9] sc1
	global_load_dword v1, v17, s[10:11] sc1
	global_load_dword v2, v17, s[12:13] sc1
	global_load_dword v3, v17, s[14:15] sc1
	global_load_dword v4, v17, s[16:17] sc1
	global_load_dword v5, v17, s[18:19] sc1
	global_load_dword v6, v17, s[20:21] sc1
	global_load_dword v7, v17, s[22:23] sc1
	global_load_dword v8, v17, s[24:25] sc1
	global_load_dword v9, v17, s[26:27] sc1
	global_load_dword v10, v17, s[28:29] sc1
	global_load_dword v11, v17, s[30:31] sc1
	global_load_dword v12, v17, s[34:35] sc1
	global_load_dword v13, v17, s[36:37] sc1
	global_load_dword v14, v17, s[38:39] sc1
	global_load_dword v15, v17, s[40:41] sc1
	s_mov_b64 s[42:43], -1
	s_mov_b64 s[44:45], -1
	s_waitcnt vmcnt(14)
	v_add_u32_e32 v18, v1, v16
	s_waitcnt vmcnt(13)
	v_add_u32_e32 v18, v18, v2
	s_waitcnt vmcnt(12)
	v_add_u32_e32 v18, v18, v3
	s_waitcnt vmcnt(11)
	v_add_u32_e32 v18, v18, v4
	s_waitcnt vmcnt(10)
	v_add_u32_e32 v18, v18, v5
	s_waitcnt vmcnt(9)
	v_add_u32_e32 v18, v18, v6
	s_waitcnt vmcnt(8)
	v_add_u32_e32 v18, v18, v7
	s_waitcnt vmcnt(7)
	v_add_u32_e32 v18, v18, v8
	s_waitcnt vmcnt(6)
	v_add_u32_e32 v18, v18, v9
	s_waitcnt vmcnt(5)
	v_add_u32_e32 v18, v18, v10
	s_waitcnt vmcnt(4)
	v_add_u32_e32 v18, v18, v11
	s_waitcnt vmcnt(3)
	v_add_u32_e32 v18, v18, v12
	s_waitcnt vmcnt(2)
	v_add_u32_e32 v18, v18, v13
	s_waitcnt vmcnt(1)
	v_add_u32_e32 v18, v18, v14
	s_waitcnt vmcnt(0)
	v_add_u32_e32 v18, v18, v15
	v_cmp_eq_u32_e32 vcc, s48, v18
	s_cbranch_vccnz .LBB11_165
	s_and_b32 s42, s49, 0xff
	s_cmp_eq_u32 s42, 0
	s_mov_b64 s[42:43], -1
	s_mov_b64 s[46:47], -1
	s_sleep 4
	s_cbranch_scc0 .LBB11_170
	global_load_dword v18, v17, s[6:7] sc1
	s_waitcnt vmcnt(0)
	v_cmp_eq_u32_e32 vcc, 0, v18
	s_cbranch_vccnz .LBB11_172
	s_mov_b64 s[46:47], 0

; __device__ __forceinline__ unsigned xb_ld(unsigned* p)              { return __hip_atomic_load(p, __ATOMIC_RELAXED, __HIP_MEMORY_SCOPE_AGENT); }
; __device__ __forceinline__ unsigned xb_add(unsigned* p, unsigned v) { return __hip_atomic_fetch_add(p, v, __ATOMIC_RELAXED, __HIP_MEMORY_SCOPE_AGENT); }
; #define XB_SPIN(cond, bar) do { unsigned _sp = 0; while (cond) { __builtin_amdgcn_s_sleep(1); \
;     if ((++_sp & 255u) == 0u) { if (xb_ld(&(bar)[XB_TMO])) break; if (_sp > XB_SPIN_CAP) { atomicAdd(&(bar)[XB_TMO], 1u); break; } } } } while (0)
; __device__ __forceinline__ void xcd_barrier(const XcdBarrier& b) {
;     ...
;             else XB_SPIN(xb_ld(&bar[XB_TOPGEN]) == tg, bar);
;             __builtin_amdgcn_fence(__ATOMIC_ACQUIRE, "agent");
;             xb_add(&bar[XB_XGEN(b.x)], 1u);
;             asm volatile("s_waitcnt vmcnt(0)" ::: "memory");
;         } else {
;             XB_SPIN(xb_ld(&bar[XB_XGEN(b.x)]) == gen, bar);
.LBB11_184:
	s_and_b32 s20, s24, 0xff
	s_mov_b64 s[18:19], -1
	s_cmp_lg_u32 s20, 0
	s_mov_b64 s[22:23], -1
	s_sleep 4
	s_cbranch_scc1 .LBB11_187
	global_load_dword v3, v1, s[6:7] sc1
	s_waitcnt vmcnt(0)
	v_cmp_eq_u32_e32 vcc, 0, v3
	s_cbranch_vccnz .LBB11_189
	s_mov_b64 s[22:23], 0
	s_mov_b64 s[20:21], -1

; __device__ __forceinline__ unsigned xb_ld(unsigned* p)              { return __hip_atomic_load(p, __ATOMIC_RELAXED, __HIP_MEMORY_SCOPE_AGENT); }
; __device__ __forceinline__ unsigned xb_add(unsigned* p, unsigned v) { return __hip_atomic_fetch_add(p, v, __ATOMIC_RELAXED, __HIP_MEMORY_SCOPE_AGENT); }
; #define XB_SPIN(cond, bar) do { unsigned _sp = 0; while (cond) { __builtin_amdgcn_s_sleep(1); \
;     if ((++_sp & 255u) == 0u) { if (xb_ld(&(bar)[XB_TMO])) break; if (_sp > XB_SPIN_CAP) { atomicAdd(&(bar)[XB_TMO], 1u); break; } } } } while (0)
; __device__ __forceinline__ void xcd_barrier(const XcdBarrier& b) {
;     ...
;             else XB_SPIN(xb_ld(&bar[XB_TOPGEN]) == tg, bar);
;             __builtin_amdgcn_fence(__ATOMIC_ACQUIRE, "agent");
;             xb_add(&bar[XB_XGEN(b.x)], 1u);
;             asm volatile("s_waitcnt vmcnt(0)" ::: "memory");
;         } else {
;             XB_SPIN(xb_ld(&bar[XB_XGEN(b.x)]) == gen, bar);
.LBB11_201:
	s_and_b32 s20, s26, 0xff
	s_cmp_lg_u32 s20, 0
	s_mov_b64 s[22:23], -1
	s_sleep 4
	s_cbranch_scc1 .LBB11_204
	global_load_dword v2, v1, s[6:7] sc1
	s_waitcnt vmcnt(0)
	v_cmp_eq_u32_e32 vcc, 0, v2
	s_cbranch_vccnz .LBB11_206
	s_mov_b64 s[22:23], 0
	s_mov_b64 s[20:21], -1

; __device__ __forceinline__ unsigned xb_ld(unsigned* p)              { return __hip_atomic_load(p, __ATOMIC_RELAXED, __HIP_MEMORY_SCOPE_AGENT); }
; __device__ __forceinline__ void xcd_barrier_complete(unsigned* bar, unsigned x, unsigned& nloc, unsigned& nx) {
;     const unsigned G = gridDim.x * gridDim.y * gridDim.z;
;     unsigned sum, cnt, mine, sp = 0u;
;     for (;;) {
;         sum = 0u; cnt = 0u; mine = 0u;
; #pragma unroll
;         for (unsigned j = 0; j < 16; ++j) { const unsigned c = xb_ld(&bar[XB_XCNT(j)]); sum += c; cnt += (c > 0u) ? 1u : 0u; mine = (j == x) ? c : mine; }
;         if (sum == G) break;
;         __builtin_amdgcn_s_sleep(1);
;         if ((++sp & 255u) == 0u) { if (xb_ld(&bar[XB_TMO])) break; if (sp > XB_SPIN_CAP) { atomicAdd(&bar[XB_TMO], 1u); break; } }
;     }
.LBB11_367:
	v_readlane_b32 s6, v249, 45
	v_readlane_b32 s7, v249, 46
	s_mov_b64 s[8:9], -1
	s_nop 3
	global_load_dword v1, v3, s[6:7] sc1
	v_readlane_b32 s6, v249, 47
	v_readlane_b32 s7, v249, 48
	s_nop 4
	global_load_dword v2, v3, s[6:7] sc1
	v_readlane_b32 s6, v249, 49
	v_readlane_b32 s7, v249, 50
	s_waitcnt vmcnt(0)
	v_add_u32_e32 v18, v2, v1
	s_nop 2
	global_load_dword v4, v3, s[6:7] sc1
	v_readlane_b32 s6, v249, 51
	v_readlane_b32 s7, v249, 52
	s_waitcnt vmcnt(0)
	v_add_u32_e32 v18, v18, v4
	s_nop 2
	global_load_dword v5, v3, s[6:7] sc1
	v_readlane_b32 s6, v249, 53
	v_readlane_b32 s7, v249, 54
	s_waitcnt vmcnt(0)
	v_add_u32_e32 v18, v18, v5
	s_nop 2
	global_load_dword v6, v3, s[6:7] sc1
	v_readlane_b32 s6, v249, 55
	v_readlane_b32 s7, v249, 56
	s_waitcnt vmcnt(0)
	v_add_u32_e32 v18, v18, v6
	s_nop 2
	global_load_dword v7, v3, s[6:7] sc1
	v_readlane_b32 s6, v249, 57
	v_readlane_b32 s7, v249, 58
	s_waitcnt vmcnt(0)
	v_add_u32_e32 v18, v18, v7
	s_nop 2
	global_load_dword v8, v3, s[6:7] sc1
	v_readlane_b32 s6, v249, 59
	v_readlane_b32 s7, v249, 60
	s_waitcnt vmcnt(0)
	v_add_u32_e32 v18, v18, v8
	s_nop 2
	global_load_dword v9, v3, s[6:7] sc1
	v_readlane_b32 s6, v249, 61
	v_readlane_b32 s7, v249, 62
	s_waitcnt vmcnt(0)
	v_add_u32_e32 v18, v18, v9
	s_nop 2
	global_load_dword v10, v3, s[6:7] sc1
	v_readlane_b32 s6, v249, 63
	v_readlane_b32 s7, v250, 0
	s_waitcnt vmcnt(0)
	v_add_u32_e32 v18, v18, v10
	s_nop 2
	global_load_dword v11, v3, s[6:7] sc1
	v_readlane_b32 s6, v250, 1
	v_readlane_b32 s7, v250, 2
	s_waitcnt vmcnt(0)
	v_add_u32_e32 v18, v18, v11
	s_nop 2
	global_load_dword v12, v3, s[6:7] sc1
	v_readlane_b32 s6, v250, 3
	v_readlane_b32 s7, v250, 4
	s_waitcnt vmcnt(0)
	v_add_u32_e32 v18, v18, v12
	s_nop 2
	global_load_dword v13, v3, s[6:7] sc1
	v_readlane_b32 s6, v250, 5
	v_readlane_b32 s7, v250, 6
	s_waitcnt vmcnt(0)
	v_add_u32_e32 v18, v18, v13
	s_nop 2
	global_load_dword v14, v3, s[6:7] sc1
	v_readlane_b32 s6, v250, 7
	v_readlane_b32 s7, v250, 8
	s_waitcnt vmcnt(0)
	v_add_u32_e32 v18, v18, v14
	s_nop 2
	global_load_dword v15, v3, s[6:7] sc1
	v_readlane_b32 s6, v250, 9
	v_readlane_b32 s7, v250, 10
	s_waitcnt vmcnt(0)
	v_add_u32_e32 v18, v18, v15
	s_nop 2
	global_load_dword v16, v3, s[6:7] sc1
	v_readlane_b32 s6, v250, 11
	v_readlane_b32 s7, v250, 12
	s_waitcnt vmcnt(0)
	v_add_u32_e32 v18, v18, v16
	s_nop 2
	global_load_dword v17, v3, s[6:7] sc1
	s_mov_b64 s[6:7], -1
	s_waitcnt vmcnt(0)
	v_add_u32_e32 v18, v18, v17
	v_cmp_eq_u32_e32 vcc, s1, v18
	s_cbranch_vccnz .LBB11_366
	s_and_b32 s6, s12, 0xff
	s_cmp_eq_u32 s6, 0
	s_mov_b64 s[6:7], -1
	s_mov_b64 s[10:11], -1
	s_sleep 4
	s_cbranch_scc0 .LBB11_371
	v_readlane_b32 s6, v249, 43
	v_readlane_b32 s7, v249, 44
	s_nop 4
	global_load_dword v18, v3, s[6:7] sc1
	s_waitcnt vmcnt(0)
	v_cmp_eq_u32_e32 vcc, 0, v18
	s_cbranch_vccnz .LBB11_373
	s_mov_b64 s[10:11], 0
	s_mov_b64 s[6:7], -1

; __device__ __forceinline__ unsigned xb_ld(unsigned* p)              { return __hip_atomic_load(p, __ATOMIC_RELAXED, __HIP_MEMORY_SCOPE_AGENT); }
; __device__ __forceinline__ void xcd_barrier_complete(unsigned* bar, unsigned x, unsigned& nloc, unsigned& nx) {
;     const unsigned G = gridDim.x * gridDim.y * gridDim.z;
;     unsigned sum, cnt, mine, sp = 0u;
;     for (;;) {
;         sum = 0u; cnt = 0u; mine = 0u;
; #pragma unroll
;         for (unsigned j = 0; j < 16; ++j) { const unsigned c = xb_ld(&bar[XB_XCNT(j)]); sum += c; cnt += (c > 0u) ? 1u : 0u; mine = (j == x) ? c : mine; }
;         if (sum == G) break;
;         __builtin_amdgcn_s_sleep(1);
;         if ((++sp & 255u) == 0u) { if (xb_ld(&bar[XB_TMO])) break; if (sp > XB_SPIN_CAP) { atomicAdd(&bar[XB_TMO], 1u); break; } }
;     }
.LBB11_381:
	v_readlane_b32 s4, v249, 45
	v_readlane_b32 s5, v249, 46
	s_mov_b64 s[8:9], -1
	s_nop 3
	global_load_dword v1, v3, s[4:5] sc1
	v_readlane_b32 s4, v249, 47
	v_readlane_b32 s5, v249, 48
	s_nop 4
	global_load_dword v2, v3, s[4:5] sc1
	v_readlane_b32 s4, v249, 49
	v_readlane_b32 s5, v249, 50
	s_waitcnt vmcnt(0)
	v_add_u32_e32 v18, v2, v1
	s_nop 2
	global_load_dword v4, v3, s[4:5] sc1
	v_readlane_b32 s4, v249, 51
	v_readlane_b32 s5, v249, 52
	s_waitcnt vmcnt(0)
	v_add_u32_e32 v18, v18, v4
	s_nop 2
	global_load_dword v5, v3, s[4:5] sc1
	v_readlane_b32 s4, v249, 53
	v_readlane_b32 s5, v249, 54
	s_waitcnt vmcnt(0)
	v_add_u32_e32 v18, v18, v5
	s_nop 2
	global_load_dword v6, v3, s[4:5] sc1
	v_readlane_b32 s4, v249, 55
	v_readlane_b32 s5, v249, 56
	s_waitcnt vmcnt(0)
	v_add_u32_e32 v18, v18, v6
	s_nop 2
	global_load_dword v7, v3, s[4:5] sc1
	v_readlane_b32 s4, v249, 57
	v_readlane_b32 s5, v249, 58
	s_waitcnt vmcnt(0)
	v_add_u32_e32 v18, v18, v7
	s_nop 2
	global_load_dword v8, v3, s[4:5] sc1
	v_readlane_b32 s4, v249, 59
	v_readlane_b32 s5, v249, 60
	s_waitcnt vmcnt(0)
	v_add_u32_e32 v18, v18, v8
	s_nop 2
	global_load_dword v9, v3, s[4:5] sc1
	v_readlane_b32 s4, v249, 61
	v_readlane_b32 s5, v249, 62
	s_waitcnt vmcnt(0)
	v_add_u32_e32 v18, v18, v9
	s_nop 2
	global_load_dword v10, v3, s[4:5] sc1
	v_readlane_b32 s4, v249, 63
	v_readlane_b32 s5, v250, 0
	s_waitcnt vmcnt(0)
	v_add_u32_e32 v18, v18, v10
	s_nop 2
	global_load_dword v11, v3, s[4:5] sc1
	v_readlane_b32 s4, v250, 1
	v_readlane_b32 s5, v250, 2
	s_waitcnt vmcnt(0)
	v_add_u32_e32 v18, v18, v11
	s_nop 2
	global_load_dword v12, v3, s[4:5] sc1
	v_readlane_b32 s4, v250, 3
	v_readlane_b32 s5, v250, 4
	s_waitcnt vmcnt(0)
	v_add_u32_e32 v18, v18, v12
	s_nop 2
	global_load_dword v13, v3, s[4:5] sc1
	v_readlane_b32 s4, v250, 5
	v_readlane_b32 s5, v250, 6
	s_waitcnt vmcnt(0)
	v_add_u32_e32 v18, v18, v13
	s_nop 2
	global_load_dword v14, v3, s[4:5] sc1
	v_readlane_b32 s4, v250, 7
	v_readlane_b32 s5, v250, 8
	s_waitcnt vmcnt(0)
	v_add_u32_e32 v18, v18, v14
	s_nop 2
	global_load_dword v15, v3, s[4:5] sc1
	v_readlane_b32 s4, v250, 9
	v_readlane_b32 s5, v250, 10
	s_waitcnt vmcnt(0)
	v_add_u32_e32 v18, v18, v15
	s_nop 2
	global_load_dword v16, v3, s[4:5] sc1
	v_readlane_b32 s4, v250, 11
	v_readlane_b32 s5, v250, 12
	s_waitcnt vmcnt(0)
	v_add_u32_e32 v18, v18, v16
	s_nop 2
	global_load_dword v17, v3, s[4:5] sc1
	s_mov_b64 s[4:5], -1
	s_waitcnt vmcnt(0)
	v_add_u32_e32 v18, v18, v17
	v_cmp_eq_u32_e32 vcc, s1, v18
	s_cbranch_vccnz .LBB11_380
	s_and_b32 s4, s12, 0xff
	s_cmp_eq_u32 s4, 0
	s_mov_b64 s[4:5], -1
	s_mov_b64 s[10:11], -1
	s_sleep 4
	s_cbranch_scc0 .LBB11_385
	v_readlane_b32 s4, v249, 43
	v_readlane_b32 s5, v249, 44
	s_nop 4
	global_load_dword v18, v3, s[4:5] sc1
	s_waitcnt vmcnt(0)
	v_cmp_eq_u32_e32 vcc, 0, v18
	s_cbranch_vccnz .LBB11_387
	s_mov_b64 s[10:11], 0
	s_mov_b64 s[4:5], -1

; __device__ __forceinline__ unsigned xb_ld(unsigned* p)              { return __hip_atomic_load(p, __ATOMIC_RELAXED, __HIP_MEMORY_SCOPE_AGENT); }
; __device__ __forceinline__ unsigned xb_add(unsigned* p, unsigned v) { return __hip_atomic_fetch_add(p, v, __ATOMIC_RELAXED, __HIP_MEMORY_SCOPE_AGENT); }
; #define XB_SPIN(cond, bar) do { unsigned _sp = 0; while (cond) { __builtin_amdgcn_s_sleep(1); \
;     if ((++_sp & 255u) == 0u) { if (xb_ld(&(bar)[XB_TMO])) break; if (_sp > XB_SPIN_CAP) { atomicAdd(&(bar)[XB_TMO], 1u); break; } } } } while (0)
; __device__ __forceinline__ void xcd_barrier(const XcdBarrier& b) {
;     ...
;             else XB_SPIN(xb_ld(&bar[XB_TOPGEN]) == tg, bar);
;             __builtin_amdgcn_fence(__ATOMIC_ACQUIRE, "agent");
;             xb_add(&bar[XB_XGEN(b.x)], 1u);
;             asm volatile("s_waitcnt vmcnt(0)" ::: "memory");
;         } else {
;             XB_SPIN(xb_ld(&bar[XB_XGEN(b.x)]) == gen, bar);
.LBB11_399:
	s_and_b32 s16, s1, 0xff
	s_mov_b64 s[14:15], -1
	s_cmp_lg_u32 s16, 0
	s_mov_b64 s[18:19], -1
	s_sleep 4
	s_cbranch_scc1 .LBB11_402
	v_readlane_b32 s16, v249, 43
	v_readlane_b32 s17, v249, 44
	s_nop 4
	global_load_dword v2, v3, s[16:17] sc1
	s_waitcnt vmcnt(0)
	v_cmp_eq_u32_e32 vcc, 0, v2
	s_cbranch_vccnz .LBB11_404
	s_mov_b64 s[18:19], 0
	s_mov_b64 s[16:17], -1

; __device__ __forceinline__ unsigned xb_ld(unsigned* p)              { return __hip_atomic_load(p, __ATOMIC_RELAXED, __HIP_MEMORY_SCOPE_AGENT); }
; __device__ __forceinline__ void xcd_barrier_complete(unsigned* bar, unsigned x, unsigned& nloc, unsigned& nx) {
;     const unsigned G = gridDim.x * gridDim.y * gridDim.z;
;     unsigned sum, cnt, mine, sp = 0u;
;     for (;;) {
;         sum = 0u; cnt = 0u; mine = 0u;
; #pragma unroll
;         for (unsigned j = 0; j < 16; ++j) { const unsigned c = xb_ld(&bar[XB_XCNT(j)]); sum += c; cnt += (c > 0u) ? 1u : 0u; mine = (j == x) ? c : mine; }
;         if (sum == G) break;
;         __builtin_amdgcn_s_sleep(1);
;         if ((++sp & 255u) == 0u) { if (xb_ld(&bar[XB_TMO])) break; if (sp > XB_SPIN_CAP) { atomicAdd(&bar[XB_TMO], 1u); break; } }
;     }
.LBB11_855:
	v_readlane_b32 s4, v249, 45
	v_readlane_b32 s5, v249, 46
	s_mov_b64 s[6:7], -1
	s_nop 3
	global_load_dword v1, v3, s[4:5] sc1
	v_readlane_b32 s4, v249, 47
	v_readlane_b32 s5, v249, 48
	s_nop 4
	global_load_dword v2, v3, s[4:5] sc1
	v_readlane_b32 s4, v249, 49
	v_readlane_b32 s5, v249, 50
	s_waitcnt vmcnt(0)
	v_add_u32_e32 v18, v2, v1
	s_nop 2
	global_load_dword v4, v3, s[4:5] sc1
	v_readlane_b32 s4, v249, 51
	v_readlane_b32 s5, v249, 52
	s_waitcnt vmcnt(0)
	v_add_u32_e32 v18, v18, v4
	s_nop 2
	global_load_dword v5, v3, s[4:5] sc1
	v_readlane_b32 s4, v249, 53
	v_readlane_b32 s5, v249, 54
	s_waitcnt vmcnt(0)
	v_add_u32_e32 v18, v18, v5
	s_nop 2
	global_load_dword v6, v3, s[4:5] sc1
	v_readlane_b32 s4, v249, 55
	v_readlane_b32 s5, v249, 56
	s_waitcnt vmcnt(0)
	v_add_u32_e32 v18, v18, v6
	s_nop 2
	global_load_dword v7, v3, s[4:5] sc1
	v_readlane_b32 s4, v249, 57
	v_readlane_b32 s5, v249, 58
	s_waitcnt vmcnt(0)
	v_add_u32_e32 v18, v18, v7
	s_nop 2
	global_load_dword v8, v3, s[4:5] sc1
	v_readlane_b32 s4, v249, 59
	v_readlane_b32 s5, v249, 60
	s_waitcnt vmcnt(0)
	v_add_u32_e32 v18, v18, v8
	s_nop 2
	global_load_dword v9, v3, s[4:5] sc1
	v_readlane_b32 s4, v249, 61
	v_readlane_b32 s5, v249, 62
	s_waitcnt vmcnt(0)
	v_add_u32_e32 v18, v18, v9
	s_nop 2
	global_load_dword v10, v3, s[4:5] sc1
	v_readlane_b32 s4, v249, 63
	v_readlane_b32 s5, v250, 0
	s_waitcnt vmcnt(0)
	v_add_u32_e32 v18, v18, v10
	s_nop 2
	global_load_dword v11, v3, s[4:5] sc1
	v_readlane_b32 s4, v250, 1
	v_readlane_b32 s5, v250, 2
	s_waitcnt vmcnt(0)
	v_add_u32_e32 v18, v18, v11
	s_nop 2
	global_load_dword v12, v3, s[4:5] sc1
	v_readlane_b32 s4, v250, 3
	v_readlane_b32 s5, v250, 4
	s_waitcnt vmcnt(0)
	v_add_u32_e32 v18, v18, v12
	s_nop 2
	global_load_dword v13, v3, s[4:5] sc1
	v_readlane_b32 s4, v250, 5
	v_readlane_b32 s5, v250, 6
	s_waitcnt vmcnt(0)
	v_add_u32_e32 v18, v18, v13
	s_nop 2
	global_load_dword v14, v3, s[4:5] sc1
	v_readlane_b32 s4, v250, 7
	v_readlane_b32 s5, v250, 8
	s_waitcnt vmcnt(0)
	v_add_u32_e32 v18, v18, v14
	s_nop 2
	global_load_dword v15, v3, s[4:5] sc1
	v_readlane_b32 s4, v250, 9
	v_readlane_b32 s5, v250, 10
	s_waitcnt vmcnt(0)
	v_add_u32_e32 v18, v18, v15
	s_nop 2
	global_load_dword v16, v3, s[4:5] sc1
	v_readlane_b32 s4, v250, 11
	v_readlane_b32 s5, v250, 12
	s_waitcnt vmcnt(0)
	v_add_u32_e32 v18, v18, v16
	s_nop 2
	global_load_dword v17, v3, s[4:5] sc1
	s_mov_b64 s[4:5], -1
	s_waitcnt vmcnt(0)
	v_add_u32_e32 v18, v18, v17
	v_cmp_eq_u32_e32 vcc, s1, v18
	s_cbranch_vccnz .LBB11_854
	s_and_b32 s4, s10, 0xff
	s_cmp_eq_u32 s4, 0
	s_mov_b64 s[4:5], -1
	s_mov_b64 s[8:9], -1
	s_sleep 4
	s_cbranch_scc0 .LBB11_859
	v_readlane_b32 s4, v249, 43
	v_readlane_b32 s5, v249, 44
	s_nop 4
	global_load_dword v18, v3, s[4:5] sc1
	s_waitcnt vmcnt(0)
	v_cmp_eq_u32_e32 vcc, 0, v18
	s_cbranch_vccnz .LBB11_861
	s_mov_b64 s[8:9], 0
	s_mov_b64 s[4:5], -1

; __device__ __forceinline__ unsigned xb_ld(unsigned* p)              { return __hip_atomic_load(p, __ATOMIC_RELAXED, __HIP_MEMORY_SCOPE_AGENT); }
; __device__ __forceinline__ unsigned xb_add(unsigned* p, unsigned v) { return __hip_atomic_fetch_add(p, v, __ATOMIC_RELAXED, __HIP_MEMORY_SCOPE_AGENT); }
; #define XB_SPIN(cond, bar) do { unsigned _sp = 0; while (cond) { __builtin_amdgcn_s_sleep(1); \
;     if ((++_sp & 255u) == 0u) { if (xb_ld(&(bar)[XB_TMO])) break; if (_sp > XB_SPIN_CAP) { atomicAdd(&(bar)[XB_TMO], 1u); break; } } } } while (0)
; __device__ __forceinline__ void xcd_barrier(const XcdBarrier& b) {
;     ...
;             else XB_SPIN(xb_ld(&bar[XB_TOPGEN]) == tg, bar);
;             __builtin_amdgcn_fence(__ATOMIC_ACQUIRE, "agent");
;             xb_add(&bar[XB_XGEN(b.x)], 1u);
;             asm volatile("s_waitcnt vmcnt(0)" ::: "memory");
;         } else {
;             XB_SPIN(xb_ld(&bar[XB_XGEN(b.x)]) == gen, bar);
.LBB11_873:
	s_and_b32 s14, s1, 0xff
	s_mov_b64 s[12:13], -1
	s_cmp_lg_u32 s14, 0
	s_mov_b64 s[16:17], -1
	s_sleep 4
	s_cbranch_scc1 .LBB11_876
	v_readlane_b32 s14, v249, 43
	v_readlane_b32 s15, v249, 44
	s_nop 4
	global_load_dword v2, v3, s[14:15] sc1
	s_waitcnt vmcnt(0)
	v_cmp_eq_u32_e32 vcc, 0, v2
	s_cbranch_vccnz .LBB11_878
	s_mov_b64 s[16:17], 0
	s_mov_b64 s[14:15], -1

; __device__ __forceinline__ unsigned xb_ld(unsigned* p)              { return __hip_atomic_load(p, __ATOMIC_RELAXED, __HIP_MEMORY_SCOPE_AGENT); }
; __device__ __forceinline__ void xcd_barrier_complete(unsigned* bar, unsigned x, unsigned& nloc, unsigned& nx) {
;     const unsigned G = gridDim.x * gridDim.y * gridDim.z;
;     unsigned sum, cnt, mine, sp = 0u;
;     for (;;) {
;         sum = 0u; cnt = 0u; mine = 0u;
; #pragma unroll
;         for (unsigned j = 0; j < 16; ++j) { const unsigned c = xb_ld(&bar[XB_XCNT(j)]); sum += c; cnt += (c > 0u) ? 1u : 0u; mine = (j == x) ? c : mine; }
;         if (sum == G) break;
;         __builtin_amdgcn_s_sleep(1);
;         if ((++sp & 255u) == 0u) { if (xb_ld(&bar[XB_TMO])) break; if (sp > XB_SPIN_CAP) { atomicAdd(&bar[XB_TMO], 1u); break; } }
;     }
.LBB11_1674:
	v_readlane_b32 s4, v249, 45
	v_readlane_b32 s5, v249, 46
	s_mov_b64 s[14:15], -1
	s_nop 3
	global_load_dword v1, v3, s[4:5] sc1
	v_readlane_b32 s4, v249, 47
	v_readlane_b32 s5, v249, 48
	s_nop 4
	global_load_dword v2, v3, s[4:5] sc1
	v_readlane_b32 s4, v249, 49
	v_readlane_b32 s5, v249, 50
	s_waitcnt vmcnt(0)
	v_add_u32_e32 v18, v2, v1
	s_nop 2
	global_load_dword v4, v3, s[4:5] sc1
	v_readlane_b32 s4, v249, 51
	v_readlane_b32 s5, v249, 52
	s_waitcnt vmcnt(0)
	v_add_u32_e32 v18, v18, v4
	s_nop 2
	global_load_dword v5, v3, s[4:5] sc1
	v_readlane_b32 s4, v249, 53
	v_readlane_b32 s5, v249, 54
	s_waitcnt vmcnt(0)
	v_add_u32_e32 v18, v18, v5
	s_nop 2
	global_load_dword v6, v3, s[4:5] sc1
	v_readlane_b32 s4, v249, 55
	v_readlane_b32 s5, v249, 56
	s_waitcnt vmcnt(0)
	v_add_u32_e32 v18, v18, v6
	s_nop 2
	global_load_dword v7, v3, s[4:5] sc1
	v_readlane_b32 s4, v249, 57
	v_readlane_b32 s5, v249, 58
	s_waitcnt vmcnt(0)
	v_add_u32_e32 v18, v18, v7
	s_nop 2
	global_load_dword v8, v3, s[4:5] sc1
	v_readlane_b32 s4, v249, 59
	v_readlane_b32 s5, v249, 60
	s_waitcnt vmcnt(0)
	v_add_u32_e32 v18, v18, v8
	s_nop 2
	global_load_dword v9, v3, s[4:5] sc1
	v_readlane_b32 s4, v249, 61
	v_readlane_b32 s5, v249, 62
	s_waitcnt vmcnt(0)
	v_add_u32_e32 v18, v18, v9
	s_nop 2
	global_load_dword v10, v3, s[4:5] sc1
	v_readlane_b32 s4, v249, 63
	v_readlane_b32 s5, v250, 0
	s_waitcnt vmcnt(0)
	v_add_u32_e32 v18, v18, v10
	s_nop 2
	global_load_dword v11, v3, s[4:5] sc1
	v_readlane_b32 s4, v250, 1
	v_readlane_b32 s5, v250, 2
	s_waitcnt vmcnt(0)
	v_add_u32_e32 v18, v18, v11
	s_nop 2
	global_load_dword v12, v3, s[4:5] sc1
	v_readlane_b32 s4, v250, 3
	v_readlane_b32 s5, v250, 4
	s_waitcnt vmcnt(0)
	v_add_u32_e32 v18, v18, v12
	s_nop 2
	global_load_dword v13, v3, s[4:5] sc1
	v_readlane_b32 s4, v250, 5
	v_readlane_b32 s5, v250, 6
	s_waitcnt vmcnt(0)
	v_add_u32_e32 v18, v18, v13
	s_nop 2
	global_load_dword v14, v3, s[4:5] sc1
	v_readlane_b32 s4, v250, 7
	v_readlane_b32 s5, v250, 8
	s_waitcnt vmcnt(0)
	v_add_u32_e32 v18, v18, v14
	s_nop 2
	global_load_dword v15, v3, s[4:5] sc1
	v_readlane_b32 s4, v250, 9
	v_readlane_b32 s5, v250, 10
	s_waitcnt vmcnt(0)
	v_add_u32_e32 v18, v18, v15
	s_nop 2
	global_load_dword v16, v3, s[4:5] sc1
	v_readlane_b32 s4, v250, 11
	v_readlane_b32 s5, v250, 12
	s_waitcnt vmcnt(0)
	v_add_u32_e32 v18, v18, v16
	s_nop 2
	global_load_dword v17, v3, s[4:5] sc1
	s_mov_b64 s[4:5], -1
	s_waitcnt vmcnt(0)
	v_add_u32_e32 v18, v18, v17
	v_cmp_eq_u32_e32 vcc, s1, v18
	s_cbranch_vccnz .LBB11_1673
	s_and_b32 s4, s13, 0xff
	s_cmp_eq_u32 s4, 0
	s_mov_b64 s[4:5], -1
	s_mov_b64 s[16:17], -1
	s_sleep 4
	s_cbranch_scc0 .LBB11_1678
	v_readlane_b32 s4, v249, 43
	v_readlane_b32 s5, v249, 44
	s_nop 4
	global_load_dword v18, v3, s[4:5] sc1
	s_waitcnt vmcnt(0)
	v_cmp_eq_u32_e32 vcc, 0, v18
	s_cbranch_vccnz .LBB11_1680
	s_mov_b64 s[16:17], 0
	s_mov_b64 s[4:5], -1

; __device__ __forceinline__ unsigned xb_ld(unsigned* p)              { return __hip_atomic_load(p, __ATOMIC_RELAXED, __HIP_MEMORY_SCOPE_AGENT); }
; __device__ __forceinline__ unsigned xb_add(unsigned* p, unsigned v) { return __hip_atomic_fetch_add(p, v, __ATOMIC_RELAXED, __HIP_MEMORY_SCOPE_AGENT); }
; #define XB_SPIN(cond, bar) do { unsigned _sp = 0; while (cond) { __builtin_amdgcn_s_sleep(1); \
;     if ((++_sp & 255u) == 0u) { if (xb_ld(&(bar)[XB_TMO])) break; if (_sp > XB_SPIN_CAP) { atomicAdd(&(bar)[XB_TMO], 1u); break; } } } } while (0)
; __device__ __forceinline__ void xcd_barrier(const XcdBarrier& b) {
;     ...
;             else XB_SPIN(xb_ld(&bar[XB_TOPGEN]) == tg, bar);
;             __builtin_amdgcn_fence(__ATOMIC_ACQUIRE, "agent");
;             xb_add(&bar[XB_XGEN(b.x)], 1u);
;             asm volatile("s_waitcnt vmcnt(0)" ::: "memory");
;         } else {
;             XB_SPIN(xb_ld(&bar[XB_XGEN(b.x)]) == gen, bar);
.LBB11_1692:
	s_and_b32 s13, s1, 0xff
	s_mov_b64 s[20:21], -1
	s_cmp_lg_u32 s13, 0
	s_mov_b64 s[24:25], -1
	s_sleep 4
	s_cbranch_scc1 .LBB11_1695
	v_readlane_b32 s22, v249, 43
	v_readlane_b32 s23, v249, 44
	s_nop 4
	global_load_dword v2, v3, s[22:23] sc1
	s_waitcnt vmcnt(0)
	v_cmp_eq_u32_e32 vcc, 0, v2
	s_cbranch_vccnz .LBB11_1697
	s_mov_b64 s[24:25], 0
	s_mov_b64 s[22:23], -1
